# split-K slab epilogues of P2/P10/P13 skip the stores of panel-33 padding rows (nobody reads them)
# speedup vs baseline: 1.0047x; 1.0047x over previous
.LBB0_387:
	s_and_b64 vcc, exec, s[0:1]
	s_cbranch_vccz .LBB0_386
	s_lshl_b64 s[0:1], s[10:11], 18
	v_readlane_b32 s4, v254, 43
	v_readlane_b32 s5, v254, 44
	s_add_u32 s0, s4, s0
	v_or_b32_e32 v208, s83, v210
	s_addc_u32 s1, s5, s1
	v_lshlrev_b64 v[128:129], 10, v[208:209]
	v_lshl_add_u64 v[128:129], s[0:1], 0, v[128:129]
	s_mov_b32 s41, s11
	v_lshlrev_b32_e32 v130, 3, v176
	v_lshl_add_u64 v[128:129], v[128:129], 0, s[40:41]
	v_ashrrev_i32_e32 v131, 31, v130
	v_lshl_add_u64 v[128:129], v[130:131], 2, v[128:129]
	s_movk_i32 s0, 0x4000
	s_cmp_eq_u32 s7, 33
	s_cselect_b32 s1, 1, 0
	s_cbranch_scc0 .Lslabskip_p2_full
	s_cmp_lg_u32 s83, 0
	s_cbranch_scc1 .Lslabskip_p2_end
.Lslabskip_p2_full:
	global_store_dwordx4 v[128:129], v[124:127], off
	global_store_dwordx4 v[128:129], v[120:123], off offset:16
	global_store_dwordx4 v[128:129], v[116:119], off offset:512
	global_store_dwordx4 v[128:129], v[112:115], off offset:528
	v_readlane_b32 s4, v254, 33
	v_readlane_b32 s7, v254, 36
	v_add_co_u32_e32 v112, vcc, s0, v128
	s_mov_b32 s0, 0x8000
	s_nop 0
	v_addc_co_u32_e32 v113, vcc, 0, v129, vcc
	global_store_dwordx4 v[112:113], v[108:111], off
	global_store_dwordx4 v[112:113], v[104:107], off offset:16
	global_store_dwordx4 v[112:113], v[100:103], off offset:512
	global_store_dwordx4 v[112:113], v[96:99], off offset:528
	v_readlane_b32 s5, v254, 34
	v_readlane_b32 s6, v254, 35
	v_add_co_u32_e32 v96, vcc, s0, v128
	s_mov_b32 s0, 0xc000
	s_nop 0
	v_addc_co_u32_e32 v97, vcc, 0, v129, vcc
	global_store_dwordx4 v[96:97], v[92:95], off
	global_store_dwordx4 v[96:97], v[88:91], off offset:16
	global_store_dwordx4 v[96:97], v[84:87], off offset:512
	global_store_dwordx4 v[96:97], v[80:83], off offset:528
	s_nop 1
	v_add_co_u32_e32 v80, vcc, s0, v128
	s_mov_b32 s0, 0x24000
	s_nop 0
	v_addc_co_u32_e32 v81, vcc, 0, v129, vcc
	global_store_dwordx4 v[80:81], v[76:79], off
	global_store_dwordx4 v[80:81], v[72:75], off offset:16
	global_store_dwordx4 v[80:81], v[68:71], off offset:512
	global_store_dwordx4 v[80:81], v[64:67], off offset:528
	s_cmp_lg_u32 s1, 0
	s_cbranch_scc1 .Lslabskip_p2_end
	s_nop 1
	v_add_co_u32_e32 v64, vcc, s7, v128
	s_nop 1
	v_addc_co_u32_e32 v65, vcc, 0, v129, vcc
	global_store_dwordx4 v[64:65], v[60:63], off
	global_store_dwordx4 v[64:65], v[56:59], off offset:16
	global_store_dwordx4 v[64:65], v[52:55], off offset:512
	global_store_dwordx4 v[64:65], v[48:51], off offset:528
	s_nop 1
	v_add_co_u32_e32 v48, vcc, s0, v128
	s_nop 1
	v_addc_co_u32_e32 v49, vcc, 0, v129, vcc
	global_store_dwordx4 v[48:49], v[44:47], off
	global_store_dwordx4 v[48:49], v[40:43], off offset:16
	global_store_dwordx4 v[48:49], v[36:39], off offset:512
	global_store_dwordx4 v[48:49], v[32:35], off offset:528
	s_nop 1
	v_add_co_u32_e32 v32, vcc, 0x28000, v128
	s_nop 1
	v_addc_co_u32_e32 v33, vcc, 0, v129, vcc
	global_store_dwordx4 v[32:33], v[28:31], off
	global_store_dwordx4 v[32:33], v[24:27], off offset:16
	global_store_dwordx4 v[32:33], v[20:23], off offset:512
	global_store_dwordx4 v[32:33], v[16:19], off offset:528
	s_nop 1
	v_add_co_u32_e32 v16, vcc, 0x2c000, v128
	s_nop 1
	v_addc_co_u32_e32 v17, vcc, 0, v129, vcc
	global_store_dwordx4 v[16:17], v[12:15], off
	global_store_dwordx4 v[16:17], v[8:11], off offset:16
	global_store_dwordx4 v[16:17], v[4:7], off offset:512
	global_store_dwordx4 v[16:17], v[0:3], off offset:528
.Lslabskip_p2_end:
	s_andn2_b64 vcc, exec, s[70:71]
	s_mov_b64 s[0:1], -1
	s_cbranch_vccnz .LBB0_305
.LBB0_389:
	s_cmp_lt_i32 s13, 0
	s_cselect_b32 s61, s72, s13
	s_andn2_b64 vcc, exec, s[46:47]
	s_cbranch_vccnz .LBB0_304
	s_barrier
	s_branch .LBB0_304

.LBB0_1404:
	s_lshl_b64 s[14:15], s[0:1], 18
	v_readlane_b32 s22, v254, 43
	v_readlane_b32 s23, v254, 44
	s_add_u32 s14, s22, s14
	v_or_b32_e32 v130, s41, v130
	s_addc_u32 s15, s23, s15
	v_lshlrev_b64 v[132:133], 10, v[130:131]
	v_lshl_add_u64 v[132:133], s[14:15], 0, v[132:133]
	s_mov_b32 s11, s1
	v_lshlrev_b32_e32 v134, 3, v147
	v_lshl_add_u64 v[132:133], v[132:133], 0, s[10:11]
	v_ashrrev_i32_e32 v135, 31, v134
	v_lshl_add_u64 v[132:133], v[134:135], 2, v[132:133]
	s_movk_i32 s0, 0x4000
	s_cmp_eq_u32 s56, 33
	s_cselect_b32 s11, 1, 0
	s_cbranch_scc0 .Lslabskip_p10_full
	s_cmp_lg_u32 s41, 0
	s_cbranch_scc1 .Lslabskip_p10_end
.Lslabskip_p10_full:
	global_store_dwordx4 v[132:133], v[124:127], off
	global_store_dwordx4 v[132:133], v[120:123], off offset:16
	global_store_dwordx4 v[132:133], v[116:119], off offset:512
	global_store_dwordx4 v[132:133], v[112:115], off offset:528
	s_nop 1
	v_add_co_u32_e32 v112, vcc, s0, v132
	s_mov_b32 s0, 0x8000
	s_nop 0
	v_addc_co_u32_e32 v113, vcc, 0, v133, vcc
	global_store_dwordx4 v[112:113], v[108:111], off
	global_store_dwordx4 v[112:113], v[104:107], off offset:16
	global_store_dwordx4 v[112:113], v[100:103], off offset:512
	global_store_dwordx4 v[112:113], v[96:99], off offset:528
	s_nop 1
	v_add_co_u32_e32 v96, vcc, s0, v132
	s_mov_b32 s0, 0xc000
	s_nop 0
	v_addc_co_u32_e32 v97, vcc, 0, v133, vcc
	global_store_dwordx4 v[96:97], v[92:95], off
	global_store_dwordx4 v[96:97], v[88:91], off offset:16
	global_store_dwordx4 v[96:97], v[84:87], off offset:512
	global_store_dwordx4 v[96:97], v[80:83], off offset:528
	s_nop 1
	v_add_co_u32_e32 v80, vcc, s0, v132
	s_mov_b32 s0, 0x24000
	s_nop 0
	v_addc_co_u32_e32 v81, vcc, 0, v133, vcc
	global_store_dwordx4 v[80:81], v[76:79], off
	global_store_dwordx4 v[80:81], v[72:75], off offset:16
	global_store_dwordx4 v[80:81], v[68:71], off offset:512
	global_store_dwordx4 v[80:81], v[64:67], off offset:528
	s_cmp_lg_u32 s11, 0
	s_cbranch_scc1 .Lslabskip_p10_end
	s_nop 1
	v_add_co_u32_e32 v64, vcc, s63, v132
	s_nop 1
	v_addc_co_u32_e32 v65, vcc, 0, v133, vcc
	global_store_dwordx4 v[64:65], v[60:63], off
	global_store_dwordx4 v[64:65], v[56:59], off offset:16
	global_store_dwordx4 v[64:65], v[52:55], off offset:512
	global_store_dwordx4 v[64:65], v[48:51], off offset:528
	s_nop 1
	v_add_co_u32_e32 v48, vcc, s0, v132
	s_nop 1
	v_addc_co_u32_e32 v49, vcc, 0, v133, vcc
	global_store_dwordx4 v[48:49], v[44:47], off
	global_store_dwordx4 v[48:49], v[40:43], off offset:16
	global_store_dwordx4 v[48:49], v[36:39], off offset:512
	global_store_dwordx4 v[48:49], v[32:35], off offset:528
	s_nop 1
	v_add_co_u32_e32 v32, vcc, 0x28000, v132
	s_nop 1
	v_addc_co_u32_e32 v33, vcc, 0, v133, vcc
	global_store_dwordx4 v[32:33], v[28:31], off
	global_store_dwordx4 v[32:33], v[24:27], off offset:16
	global_store_dwordx4 v[32:33], v[20:23], off offset:512
	global_store_dwordx4 v[32:33], v[16:19], off offset:528
	s_nop 1
	v_add_co_u32_e32 v16, vcc, 0x2c000, v132
	s_nop 1
	v_addc_co_u32_e32 v17, vcc, 0, v133, vcc
	global_store_dwordx4 v[16:17], v[12:15], off
	global_store_dwordx4 v[16:17], v[8:11], off offset:16
	global_store_dwordx4 v[16:17], v[4:7], off offset:512
	global_store_dwordx4 v[16:17], v[0:3], off offset:528
.Lslabskip_p10_end:
	s_andn2_b64 vcc, exec, s[12:13]
	s_mov_b64 s[12:13], -1
	s_cbranch_vccnz .LBB0_1385
.LBB0_1405:
	s_cmp_lt_i32 s52, 0
	s_cselect_b32 s57, s2, s52
	s_andn2_b64 vcc, exec, s[4:5]
	s_cbranch_vccnz .LBB0_1384
	s_barrier
	s_branch .LBB0_1384

.LBB0_1668:
	s_lshl_b64 s[22:23], s[0:1], 18
	v_readlane_b32 s26, v254, 43
	v_readlane_b32 s27, v254, 44
	s_add_u32 s22, s26, s22
	v_or_b32_e32 v134, s46, v134
	s_addc_u32 s23, s27, s23
	v_lshlrev_b64 v[128:129], 10, v[134:135]
	v_lshl_add_u64 v[128:129], s[22:23], 0, v[128:129]
	s_mov_b32 s21, s1
	v_lshlrev_b32_e32 v130, 3, v154
	v_lshl_add_u64 v[128:129], v[128:129], 0, s[20:21]
	v_ashrrev_i32_e32 v131, 31, v130
	v_lshl_add_u64 v[128:129], v[130:131], 2, v[128:129]
	s_cmp_eq_u32 s67, 33
	s_cselect_b32 s0, 1, 0
	s_cbranch_scc0 .Lslabskip_p13_full
	s_cmp_lg_u32 s46, 0
	s_cbranch_scc1 .Lslabskip_p13_end
.Lslabskip_p13_full:
	global_store_dwordx4 v[128:129], v[124:127], off
	global_store_dwordx4 v[128:129], v[120:123], off offset:16
	global_store_dwordx4 v[128:129], v[116:119], off offset:512
	global_store_dwordx4 v[128:129], v[112:115], off offset:528
	s_nop 1
	v_add_co_u32_e32 v112, vcc, s38, v128
	s_nop 1
	v_addc_co_u32_e32 v113, vcc, 0, v129, vcc
	global_store_dwordx4 v[112:113], v[108:111], off
	global_store_dwordx4 v[112:113], v[104:107], off offset:16
	global_store_dwordx4 v[112:113], v[100:103], off offset:512
	global_store_dwordx4 v[112:113], v[96:99], off offset:528
	s_nop 1
	v_add_co_u32_e32 v96, vcc, s52, v128
	s_nop 1
	v_addc_co_u32_e32 v97, vcc, 0, v129, vcc
	global_store_dwordx4 v[96:97], v[92:95], off
	global_store_dwordx4 v[96:97], v[88:91], off offset:16
	global_store_dwordx4 v[96:97], v[84:87], off offset:512
	global_store_dwordx4 v[96:97], v[80:83], off offset:528
	s_nop 1
	v_add_co_u32_e32 v80, vcc, s53, v128
	s_nop 1
	v_addc_co_u32_e32 v81, vcc, 0, v129, vcc
	global_store_dwordx4 v[80:81], v[76:79], off
	global_store_dwordx4 v[80:81], v[72:75], off offset:16
	global_store_dwordx4 v[80:81], v[68:71], off offset:512
	global_store_dwordx4 v[80:81], v[64:67], off offset:528
	s_cmp_lg_u32 s0, 0
	s_cbranch_scc1 .Lslabskip_p13_end
	s_nop 1
	v_add_co_u32_e32 v64, vcc, s75, v128
	s_nop 1
	v_addc_co_u32_e32 v65, vcc, 0, v129, vcc
	global_store_dwordx4 v[64:65], v[60:63], off
	global_store_dwordx4 v[64:65], v[56:59], off offset:16
	global_store_dwordx4 v[64:65], v[52:55], off offset:512
	global_store_dwordx4 v[64:65], v[48:51], off offset:528
	s_nop 1
	v_add_co_u32_e32 v48, vcc, s60, v128
	s_nop 1
	v_addc_co_u32_e32 v49, vcc, 0, v129, vcc
	global_store_dwordx4 v[48:49], v[44:47], off
	global_store_dwordx4 v[48:49], v[40:43], off offset:16
	global_store_dwordx4 v[48:49], v[36:39], off offset:512
	global_store_dwordx4 v[48:49], v[32:35], off offset:528
	s_nop 1
	v_add_co_u32_e32 v32, vcc, 0x28000, v128
	s_nop 1
	v_addc_co_u32_e32 v33, vcc, 0, v129, vcc
	global_store_dwordx4 v[32:33], v[28:31], off
	global_store_dwordx4 v[32:33], v[24:27], off offset:16
	global_store_dwordx4 v[32:33], v[20:23], off offset:512
	global_store_dwordx4 v[32:33], v[16:19], off offset:528
	s_nop 1
	v_add_co_u32_e32 v16, vcc, 0x2c000, v128
	s_nop 1
	v_addc_co_u32_e32 v17, vcc, 0, v129, vcc
	global_store_dwordx4 v[16:17], v[12:15], off
	global_store_dwordx4 v[16:17], v[8:11], off offset:16
	global_store_dwordx4 v[16:17], v[4:7], off offset:512
	global_store_dwordx4 v[16:17], v[0:3], off offset:528
.Lslabskip_p13_end:
	s_andn2_b64 vcc, exec, s[24:25]
	s_mov_b64 s[24:25], -1
	s_cbranch_vccnz .LBB0_1648
.LBB0_1669:
	s_cmp_lt_i32 s65, 0
	s_cselect_b32 s68, s39, s65
	s_andn2_b64 vcc, exec, s[4:5]
	s_cbranch_vccnz .LBB0_1647
	s_barrier
	s_branch .LBB0_1647
